# PH11 split-K owner reads the giver's write-through slab with sc1 loads; the per-wave acquire invalidate (1024 mid-phase L2 invalidates) is gone
# speedup vs baseline: 1.0166x; 1.0068x over previous
.LBB0_2574:
	s_ashr_i32 s1, s0, 31
	s_lshl_b64 s[2:3], s[0:1], 18
	s_add_u32 s1, s24, s2
	s_addc_u32 s4, s25, s3
	s_lshl_b64 s[2:3], s[12:13], 2
	s_add_u32 s14, s1, s2
	s_addc_u32 s15, s4, s3
	v_lshlrev_b32_e32 v164, 2, v171
	v_mbcnt_lo_u32_b32 v144, -1, 0
	v_mbcnt_hi_u32_b32 v144, -1, v144
	global_load_dwordx4 v[140:143], v164, s[14:15] sc1
	global_load_dwordx4 v[136:139], v164, s[14:15] offset:1024 sc1
	global_load_dwordx4 v[132:135], v164, s[14:15] offset:2048 sc1
	global_load_dwordx4 v[128:131], v164, s[14:15] offset:3072 sc1
	v_mbcnt_lo_u32_b32 v145, -1, 0
	s_lshl_b32 s1, s6, 8
	v_ashrrev_i32_e32 v146, 1, v144
	v_mbcnt_hi_u32_b32 v145, -1, v145
	s_lshl_b32 s6, s16, 8
	s_add_i32 s1, s1, s7
	v_and_b32_e32 v147, 1, v144
	v_and_b32_e32 v146, -8, v146
	v_and_b32_e32 v149, 64, v145
	s_or_b32 s6, s6, s26
	v_and_or_b32 v183, v144, 15, s1
	v_cmp_eq_u32_e64 s[2:3], 0, v147
	v_cmp_eq_u32_e64 s[4:5], 1, v147
	v_xor_b32_e32 v148, 1, v145
	v_lshlrev_b32_e32 v178, 10, v147
	v_add_u32_e32 v147, 64, v149
	v_add_u32_e32 v177, s6, v146
	v_ashrrev_i32_e32 v168, 1, v183
	v_cmp_lt_i32_e32 vcc, v148, v147
	v_lshlrev_b32_e32 v144, 1, v177
	v_cvt_f32_i32_e32 v146, v168
	v_cndmask_b32_e32 v145, v145, v148, vcc
	v_and_b32_e32 v144, 0xfffff000, v144
	v_lshlrev_b32_e32 v181, 2, v145
	v_ashrrev_i32_e32 v145, 31, v144
	v_lshlrev_b64 v[144:145], 12, v[144:145]
	v_lshl_add_u64 v[152:153], s[10:11], 0, v[144:145]
	v_mul_f32_e32 v144, 0x39800000, v146
	v_cos_f32_e32 v172, v144
	v_sin_f32_e32 v170, v144
	v_mov_b32_e32 v165, 0
	v_mov_b32_e32 v151, v165
	v_and_b32_e32 v150, 0x7f8, v177
	v_lshl_add_u64 v[150:151], v[152:153], 0, v[150:151]
	s_mov_b64 s[6:7], 0x1000000
	v_lshl_add_u64 v[162:163], v[150:151], 0, s[6:7]
	v_cmp_lt_u32_e64 s[6:7], 1, v183
	s_waitcnt vmcnt(3)
	v_and_b32_e32 v145, 0xffff0000, v141
	v_lshlrev_b32_e32 v144, 16, v141
	v_and_b32_e32 v141, 0xffff0000, v140
	v_lshlrev_b32_e32 v140, 16, v140
	v_and_b32_e32 v149, 0xffff0000, v143
	v_lshlrev_b32_e32 v148, 16, v143
	v_and_b32_e32 v155, 0xffff0000, v142
	v_lshlrev_b32_e32 v154, 16, v142
	v_pk_add_f32 v[142:143], v[124:125], v[140:141]
	v_pk_add_f32 v[146:147], v[126:127], v[144:145]
	v_pk_add_f32 v[160:161], v[120:121], v[154:155]
	v_pk_add_f32 v[166:167], v[122:123], v[148:149]
	ds_bpermute_b32 v148, v181, v143
	ds_bpermute_b32 v149, v181, v147
	ds_bpermute_b32 v174, v181, v161
	ds_bpermute_b32 v175, v181, v167
	v_mov_b32_e32 v144, v142
	v_mov_b32_e32 v145, v146
	v_mov_b32_e32 v140, v143
	v_mov_b32_e32 v141, v147
	s_and_saveexec_b64 s[16:17], s[6:7]
	s_xor_b64 s[16:17], exec, s[16:17]
	s_cbranch_execz .LBB0_2584
	s_and_saveexec_b64 s[18:19], s[4:5]
	s_xor_b64 s[18:19], exec, s[18:19]
	s_cbranch_execz .LBB0_2577
	v_mov_b32_e32 v150, v160
	v_mov_b32_e32 v151, v166
	s_waitcnt lgkmcnt(0)
	v_pk_fma_f32 v[150:151], v[170:171], v[174:175], v[150:151] op_sel_hi:[0,1,1]
	v_pk_fma_f32 v[152:153], v[170:171], v[148:149], v[144:145] op_sel_hi:[0,1,1]
	v_mov_b32_e32 v154, v161
	v_mov_b32_e32 v155, v167
	v_pk_fma_f32 v[154:155], v[172:173], v[154:155], v[150:151] op_sel_hi:[0,1,1]
	v_pk_fma_f32 v[152:153], v[172:173], v[140:141], v[152:153] op_sel_hi:[0,1,1]
	s_andn2_saveexec_b64 s[18:19], s[18:19]
	s_cbranch_execz .LBB0_2579
	s_branch .LBB0_2578

.LBB0_2614:
	s_or_b64 exec, exec, s[16:17]
	v_ashrrev_i32_e32 v145, 31, v144
	v_lshlrev_b64 v[202:203], 12, v[144:145]
	v_lshl_add_u64 v[136:137], v[162:163], 0, v[202:203]
	v_mov_b32_e32 v161, 0
	v_cvt_pk_bf16_f32 v128, v128, v129
	v_lshl_add_u64 v[136:137], v[136:137], 0, v[160:161]
	s_waitcnt lgkmcnt(3)
	v_xor_b32_e32 v132, 0x80008000, v128
	v_cvt_pk_bf16_f32 v129, v130, v131
	v_cvt_pk_bf16_f32 v130, v140, v141
	v_cvt_pk_bf16_f32 v131, v142, v143
	v_cndmask_b32_e64 v132, v132, v128, s[2:3]
	s_waitcnt lgkmcnt(2)
	v_xor_b32_e32 v133, 0x80008000, v129
	global_store_dwordx2 v[136:137], v[128:129], off
	v_sub_u32_e32 v128, 0x1000, v144
	v_cndmask_b32_e64 v133, v133, v129, s[2:3]
	v_ashrrev_i32_e32 v129, 31, v128
	v_lshlrev_b64 v[204:205], 12, v[128:129]
	v_lshl_add_u64 v[128:129], v[162:163], 0, v[204:205]
	v_lshl_add_u64 v[128:129], v[128:129], 0, v[160:161]
	global_store_dwordx2 v[128:129], v[132:133], off
	v_sub_u32_e32 v128, 0x800, v144
	v_ashrrev_i32_e32 v129, 31, v128
	v_lshlrev_b64 v[206:207], 12, v[128:129]
	v_lshl_add_u64 v[128:129], v[162:163], 0, v[206:207]
	v_lshl_add_u64 v[128:129], v[128:129], 0, v[160:161]
	global_store_dwordx2 v[128:129], v[130:131], off
	v_lshlrev_b64 v[128:129], 12, v[168:169]
	s_mov_b64 s[14:15], 0x818000
	v_lshl_add_u64 v[208:209], v[128:129], 0, s[14:15]
	v_xor_b32_e32 v134, 0x80008000, v130
	v_xor_b32_e32 v135, 0x80008000, v131
	v_lshl_add_u64 v[128:129], v[162:163], 0, v[208:209]
	v_cndmask_b32_e64 v134, v134, v130, s[2:3]
	v_cndmask_b32_e64 v135, v135, v131, s[2:3]
	s_movk_i32 s1, 0x1000
	v_lshl_add_u64 v[128:129], v[128:129], 0, v[160:161]
	global_store_dwordx2 v[128:129], v[134:135], off
	v_add_co_u32_e32 v128, vcc, s1, v166
	v_add_u32_e32 v144, 0x80, v177
	s_nop 0
	v_addc_co_u32_e32 v129, vcc, 0, v167, vcc
	global_load_dwordx4 v[140:143], v[128:129], off sc1
	global_load_dwordx4 v[136:139], v[128:129], off offset:1024 sc1
	global_load_dwordx4 v[132:135], v[128:129], off offset:2048 sc1
	s_nop 0
	global_load_dwordx4 v[128:131], v[128:129], off offset:3072 sc1
	v_lshlrev_b32_e32 v145, 1, v144
	s_waitcnt lgkmcnt(1)
	v_and_b32_e32 v150, 0x7f8, v144
	v_and_b32_e32 v144, 0xfffff000, v145
	v_ashrrev_i32_e32 v145, 31, v144
	v_lshlrev_b64 v[144:145], 12, v[144:145]
	v_lshl_add_u64 v[152:153], s[10:11], 0, v[144:145]
	s_waitcnt lgkmcnt(0)
	v_mov_b32_e32 v151, v161
	v_lshl_add_u64 v[150:151], v[152:153], 0, v[150:151]
	s_mov_b64 s[14:15], 0x1000000
	v_lshl_add_u64 v[164:165], v[150:151], 0, s[14:15]
	s_waitcnt vmcnt(3)
	v_and_b32_e32 v145, 0xffff0000, v141
	v_lshlrev_b32_e32 v144, 16, v141
	v_and_b32_e32 v141, 0xffff0000, v140
	v_lshlrev_b32_e32 v140, 16, v140
	v_and_b32_e32 v149, 0xffff0000, v143
	v_lshlrev_b32_e32 v148, 16, v143
	v_and_b32_e32 v155, 0xffff0000, v142
	v_lshlrev_b32_e32 v154, 16, v142
	v_pk_add_f32 v[142:143], v[92:93], v[140:141]
	v_pk_add_f32 v[146:147], v[94:95], v[144:145]
	v_pk_add_f32 v[210:211], v[88:89], v[154:155]
	v_pk_add_f32 v[212:213], v[90:91], v[148:149]
	ds_bpermute_b32 v148, v181, v143
	ds_bpermute_b32 v149, v181, v147
	ds_bpermute_b32 v214, v181, v211
	ds_bpermute_b32 v215, v181, v213
	v_mov_b32_e32 v144, v142
	v_mov_b32_e32 v145, v146
	v_mov_b32_e32 v140, v143
	v_mov_b32_e32 v141, v147
	s_and_saveexec_b64 s[14:15], s[6:7]
	s_xor_b64 s[6:7], exec, s[14:15]
	s_cbranch_execz .LBB0_2624
	s_and_saveexec_b64 s[14:15], s[4:5]
	s_xor_b64 s[14:15], exec, s[14:15]
	s_cbranch_execz .LBB0_2617
	v_mov_b32_e32 v150, v210
	v_mov_b32_e32 v151, v212
	s_waitcnt lgkmcnt(0)
	v_pk_fma_f32 v[150:151], v[170:171], v[214:215], v[150:151] op_sel_hi:[0,1,1]
	v_pk_fma_f32 v[152:153], v[170:171], v[148:149], v[144:145] op_sel_hi:[0,1,1]
	v_mov_b32_e32 v154, v211
	v_mov_b32_e32 v155, v213
	v_pk_fma_f32 v[154:155], v[172:173], v[154:155], v[150:151] op_sel_hi:[0,1,1]
	v_pk_fma_f32 v[152:153], v[172:173], v[140:141], v[152:153] op_sel_hi:[0,1,1]
	s_andn2_saveexec_b64 s[14:15], s[14:15]
	s_cbranch_execz .LBB0_2619
	s_branch .LBB0_2618

.LBB0_2654:
	s_or_b64 exec, exec, s[6:7]
	v_lshl_add_u64 v[136:137], v[164:165], 0, v[202:203]
	v_mov_b32_e32 v161, 0
	v_cvt_pk_bf16_f32 v128, v128, v129
	v_cvt_pk_bf16_f32 v129, v130, v131
	v_lshl_add_u64 v[136:137], v[136:137], 0, v[160:161]
	s_waitcnt lgkmcnt(3)
	v_xor_b32_e32 v132, 0x80008000, v128
	s_waitcnt lgkmcnt(2)
	v_xor_b32_e32 v133, 0x80008000, v129
	v_cvt_pk_bf16_f32 v130, v140, v141
	v_cvt_pk_bf16_f32 v131, v142, v143
	v_cndmask_b32_e64 v132, v132, v128, s[2:3]
	v_cndmask_b32_e64 v133, v133, v129, s[2:3]
	global_store_dwordx2 v[136:137], v[128:129], off
	v_lshl_add_u64 v[128:129], v[164:165], 0, v[204:205]
	v_lshl_add_u64 v[128:129], v[128:129], 0, v[160:161]
	global_store_dwordx2 v[128:129], v[132:133], off
	v_lshl_add_u64 v[128:129], v[164:165], 0, v[206:207]
	v_lshl_add_u64 v[128:129], v[128:129], 0, v[160:161]
	v_xor_b32_e32 v134, 0x80008000, v130
	v_xor_b32_e32 v135, 0x80008000, v131
	global_store_dwordx2 v[128:129], v[130:131], off
	v_lshl_add_u64 v[128:129], v[164:165], 0, v[208:209]
	v_cndmask_b32_e64 v134, v134, v130, s[2:3]
	v_cndmask_b32_e64 v135, v135, v131, s[2:3]
	v_lshl_add_u64 v[128:129], v[128:129], 0, v[160:161]
	s_movk_i32 s1, 0x2000
	global_store_dwordx2 v[128:129], v[134:135], off
	v_add_co_u32_e32 v128, vcc, s1, v166
	v_add_u32_e32 v152, 0x80, v183
	s_nop 0
	v_addc_co_u32_e32 v129, vcc, 0, v167, vcc
	global_load_dwordx4 v[140:143], v[128:129], off sc1
	global_load_dwordx4 v[136:139], v[128:129], off offset:1024 sc1
	global_load_dwordx4 v[132:135], v[128:129], off offset:2048 sc1
	s_nop 0
	global_load_dwordx4 v[128:131], v[128:129], off offset:3072 sc1
	v_ashrrev_i32_e32 v168, 1, v152
	v_cvt_f32_i32_e32 v144, v168
	v_cmp_lt_u32_e64 s[6:7], 1, v152
	v_mul_f32_e32 v144, 0x39800000, v144
	v_cos_f32_e32 v172, v144
	v_sin_f32_e32 v170, v144
	s_waitcnt vmcnt(3)
	v_and_b32_e32 v145, 0xffff0000, v141
	v_lshlrev_b32_e32 v144, 16, v141
	v_and_b32_e32 v141, 0xffff0000, v140
	v_lshlrev_b32_e32 v140, 16, v140
	s_waitcnt lgkmcnt(0)
	v_and_b32_e32 v149, 0xffff0000, v143
	v_lshlrev_b32_e32 v148, 16, v143
	v_and_b32_e32 v151, 0xffff0000, v142
	v_lshlrev_b32_e32 v150, 16, v142
	v_pk_add_f32 v[142:143], v[60:61], v[140:141]
	v_pk_add_f32 v[146:147], v[62:63], v[144:145]
	v_pk_add_f32 v[174:175], v[56:57], v[150:151]
	v_pk_add_f32 v[176:177], v[58:59], v[148:149]
	ds_bpermute_b32 v148, v181, v143
	ds_bpermute_b32 v149, v181, v147
	ds_bpermute_b32 v178, v181, v175
	ds_bpermute_b32 v179, v181, v177
	v_mov_b32_e32 v140, v142
	v_mov_b32_e32 v141, v146
	v_mov_b32_e32 v144, v143
	v_mov_b32_e32 v145, v147
	s_and_saveexec_b64 s[14:15], s[6:7]
	s_xor_b64 s[14:15], exec, s[14:15]
	s_cbranch_execz .LBB0_2664
	s_and_saveexec_b64 s[16:17], s[4:5]
	s_xor_b64 s[16:17], exec, s[16:17]
	s_cbranch_execz .LBB0_2657
	v_mov_b32_e32 v150, v174
	v_mov_b32_e32 v151, v176
	s_waitcnt lgkmcnt(0)
	v_pk_fma_f32 v[150:151], v[170:171], v[178:179], v[150:151] op_sel_hi:[0,1,1]
	v_pk_fma_f32 v[152:153], v[170:171], v[148:149], v[140:141] op_sel_hi:[0,1,1]
	v_mov_b32_e32 v154, v175
	v_mov_b32_e32 v155, v177
	v_pk_fma_f32 v[154:155], v[172:173], v[154:155], v[150:151] op_sel_hi:[0,1,1]
	v_pk_fma_f32 v[152:153], v[172:173], v[144:145], v[152:153] op_sel_hi:[0,1,1]
	s_andn2_saveexec_b64 s[16:17], s[16:17]
	s_cbranch_execz .LBB0_2659
	s_branch .LBB0_2658

.LBB0_2694:
	s_or_b64 exec, exec, s[14:15]
	v_ashrrev_i32_e32 v145, 31, v144
	v_lshlrev_b64 v[202:203], 12, v[144:145]
	v_lshl_add_u64 v[136:137], v[162:163], 0, v[202:203]
	v_mov_b32_e32 v161, 0
	v_cvt_pk_bf16_f32 v128, v128, v129
	v_lshl_add_u64 v[136:137], v[136:137], 0, v[160:161]
	s_waitcnt lgkmcnt(3)
	v_xor_b32_e32 v132, 0x80008000, v128
	v_cvt_pk_bf16_f32 v129, v130, v131
	v_cvt_pk_bf16_f32 v130, v140, v141
	v_cvt_pk_bf16_f32 v131, v142, v143
	v_cndmask_b32_e64 v132, v132, v128, s[2:3]
	s_waitcnt lgkmcnt(2)
	v_xor_b32_e32 v133, 0x80008000, v129
	global_store_dwordx2 v[136:137], v[128:129], off
	v_sub_u32_e32 v128, 0x1000, v144
	v_cndmask_b32_e64 v133, v133, v129, s[2:3]
	v_ashrrev_i32_e32 v129, 31, v128
	v_lshlrev_b64 v[204:205], 12, v[128:129]
	v_lshl_add_u64 v[128:129], v[162:163], 0, v[204:205]
	v_lshl_add_u64 v[128:129], v[128:129], 0, v[160:161]
	global_store_dwordx2 v[128:129], v[132:133], off
	v_sub_u32_e32 v128, 0x800, v144
	v_ashrrev_i32_e32 v129, 31, v128
	v_lshlrev_b64 v[206:207], 12, v[128:129]
	v_lshl_add_u64 v[128:129], v[162:163], 0, v[206:207]
	s_mov_b64 s[14:15], 0x800000
	v_lshl_add_u64 v[128:129], v[128:129], 0, v[160:161]
	v_lshl_add_u64 v[208:209], v[202:203], 0, s[14:15]
	v_xor_b32_e32 v134, 0x80008000, v130
	v_xor_b32_e32 v135, 0x80008000, v131
	global_store_dwordx2 v[128:129], v[130:131], off
	v_lshl_add_u64 v[128:129], v[162:163], 0, v[208:209]
	v_cndmask_b32_e64 v134, v134, v130, s[2:3]
	v_cndmask_b32_e64 v135, v135, v131, s[2:3]
	v_lshl_add_u64 v[128:129], v[128:129], 0, v[160:161]
	s_movk_i32 s1, 0x3000
	global_store_dwordx2 v[128:129], v[134:135], off
	v_add_co_u32_e32 v128, vcc, s1, v166
	s_nop 1
	v_addc_co_u32_e32 v129, vcc, 0, v167, vcc
	global_load_dwordx4 v[140:143], v[128:129], off sc1
	global_load_dwordx4 v[136:139], v[128:129], off offset:1024 sc1
	global_load_dwordx4 v[132:135], v[128:129], off offset:2048 sc1
	s_nop 0
	global_load_dwordx4 v[128:131], v[128:129], off offset:3072 sc1
	s_waitcnt vmcnt(3)
	v_and_b32_e32 v145, 0xffff0000, v141
	v_lshlrev_b32_e32 v144, 16, v141
	v_and_b32_e32 v141, 0xffff0000, v140
	v_lshlrev_b32_e32 v140, 16, v140
	v_and_b32_e32 v149, 0xffff0000, v143
	v_lshlrev_b32_e32 v148, 16, v143
	s_waitcnt lgkmcnt(0)
	v_and_b32_e32 v151, 0xffff0000, v142
	v_lshlrev_b32_e32 v150, 16, v142
	v_pk_add_f32 v[142:143], v[28:29], v[140:141]
	v_pk_add_f32 v[146:147], v[30:31], v[144:145]
	v_pk_add_f32 v[162:163], v[24:25], v[150:151]
	v_pk_add_f32 v[166:167], v[26:27], v[148:149]
	ds_bpermute_b32 v148, v181, v143
	ds_bpermute_b32 v149, v181, v147
	ds_bpermute_b32 v210, v181, v163
	ds_bpermute_b32 v211, v181, v167
	v_mov_b32_e32 v144, v142
	v_mov_b32_e32 v145, v146
	v_mov_b32_e32 v140, v143
	v_mov_b32_e32 v141, v147
	s_and_saveexec_b64 s[14:15], s[6:7]
	s_xor_b64 s[6:7], exec, s[14:15]
	s_cbranch_execz .LBB0_2704
	s_and_saveexec_b64 s[14:15], s[4:5]
	s_xor_b64 s[14:15], exec, s[14:15]
	s_cbranch_execz .LBB0_2697
	v_mov_b32_e32 v150, v162
	v_mov_b32_e32 v151, v166
	s_waitcnt lgkmcnt(0)
	v_pk_fma_f32 v[150:151], v[170:171], v[210:211], v[150:151] op_sel_hi:[0,1,1]
	v_pk_fma_f32 v[152:153], v[170:171], v[148:149], v[144:145] op_sel_hi:[0,1,1]
	v_mov_b32_e32 v154, v163
	v_mov_b32_e32 v155, v167
	v_pk_fma_f32 v[154:155], v[172:173], v[154:155], v[150:151] op_sel_hi:[0,1,1]
	v_pk_fma_f32 v[152:153], v[172:173], v[140:141], v[152:153] op_sel_hi:[0,1,1]
	s_andn2_saveexec_b64 s[14:15], s[14:15]
	s_cbranch_execz .LBB0_2699
	s_branch .LBB0_2698
